# P0: the 256 left-over weight items go to wave 0 of every workgroup instead of all 8 waves of the 32 workgroups on XCD 0 (per-XCD balance); on v55
# speedup vs baseline: 1.0264x; 1.0051x over previous
; #define P0_LOAD(tv_, W_, N_, k0_, n0_) do { _Pragma("unroll") for (int i = 0; i < 32; ++i) tv_[i] = __builtin_nontemporal_load(W_ + (size_t)(k0_ + 2 * i + (lane >> 5)) * N_ + n0_ + (lane & 31)); } while (0)
; __global__ void __launch_bounds__(NWAVES * 64, 2) mega_fwd(Args a) {
;     ...
;             while (it < TOT) {
;                 const int itn = it + NGW; const float* Wn = a.w_in; bf16* WTn = Win_t; int Nn = PW, k0n = 0, n0n = 0, dn0n = 0; float tvn[32];
;                 if (itn < TOT) { P0_DECODE(itn, Wn, Nn, WTn, k0n, n0n, dn0n); P0_LOAD(tvn, Wn, Nn, k0n, n0n); }
.LBB0_11:
	s_add_i32 s11, s11, s10
	s_sub_i32 s100, s11, 0x2000
	s_cmp_lt_u32 s100, 0x800
	s_cbranch_scc0 .Lp0_keep
	s_and_b32 s100, s8, 7
	s_lshr_b32 s101, s8, 3
	s_addk_i32 s101, 0x2000
	s_cmp_eq_u32 s100, 0
	s_cselect_b32 s11, s101, 0x7fff
.Lp0_keep:
	s_cmpk_gt_i32 s11, 0x20ff
	s_cselect_b64 s[14:15], -1, 0
	s_mov_b32 s20, 0
	s_and_b64 vcc, exec, s[14:15]
	v_mov_b32_e32 v67, 0
	v_mov_b32_e32 v68, 0
	v_mov_b32_e32 v69, 0
	v_mov_b32_e32 v70, 0
	v_mov_b32_e32 v71, 0
	v_mov_b32_e32 v72, 0
	v_mov_b32_e32 v73, 0
	v_mov_b32_e32 v74, 0
	v_mov_b32_e32 v59, 0
	v_mov_b32_e32 v60, 0
	v_mov_b32_e32 v61, 0
	v_mov_b32_e32 v62, 0
	v_mov_b32_e32 v63, 0
	v_mov_b32_e32 v64, 0
	v_mov_b32_e32 v65, 0
	v_mov_b32_e32 v66, 0
	v_mov_b32_e32 v58, 0
	v_mov_b32_e32 v57, 0
	v_mov_b32_e32 v56, 0
	v_mov_b32_e32 v55, 0
	v_mov_b32_e32 v54, 0
	v_mov_b32_e32 v53, 0
	v_mov_b32_e32 v52, 0
	v_mov_b32_e32 v51, 0
	v_mov_b32_e32 v50, 0
	v_mov_b32_e32 v49, 0
	v_mov_b32_e32 v48, 0
	v_mov_b32_e32 v47, 0
	v_mov_b32_e32 v46, 0
	v_mov_b32_e32 v45, 0
	v_mov_b32_e32 v44, 0
	v_mov_b32_e32 v43, 0
	s_mov_b64 s[16:17], s[6:7]
	s_mov_b32 s21, 0
	s_cbranch_vccnz .LBB0_10
	s_cmpk_lt_i32 s11, 0x1900
	v_readlane_b32 s36, v254, 0
	s_cselect_b64 s[20:21], -1, 0
	v_readlane_b32 s42, v254, 6
	v_readlane_b32 s43, v254, 7
	s_movk_i32 s13, 0x1900
	s_and_b64 vcc, exec, s[20:21]
	s_mov_b32 s22, s11
	s_mov_b64 s[16:17], s[6:7]
	s_mov_b64 s[18:19], s[42:43]
	v_readlane_b32 s37, v254, 1
	v_readlane_b32 s38, v254, 2
	v_readlane_b32 s39, v254, 3
	v_readlane_b32 s40, v254, 4
	v_readlane_b32 s41, v254, 5
	v_readlane_b32 s44, v254, 8
	v_readlane_b32 s45, v254, 9
	v_readlane_b32 s46, v254, 10
	v_readlane_b32 s47, v254, 11
	v_readlane_b32 s48, v254, 12
	v_readlane_b32 s49, v254, 13
	v_readlane_b32 s50, v254, 14
	v_readlane_b32 s51, v254, 15
	s_cbranch_vccnz .LBB0_14
	s_add_i32 s22, s11, 0xffffe700
	s_movk_i32 s13, 0x800
	s_mov_b64 s[16:17], s[72:73]
	s_waitcnt lgkmcnt(0)
	s_mov_b64 s[18:19], s[68:69]
